# sample attention: 4 waves of a WG take the 4 tokens of one (batch,head); lanes read 256B-contiguous K/V segments
# speedup vs baseline: 1.0175x; 1.0038x over previous
; __device__ __forceinline__ int fresh_tid() { int t = threadIdx.x; asm volatile("" : "+v"(t)); return t; }
; __device__ __forceinline__ void attn_sample_item(const P& p, int wi, int lane) {
;     ...
;     const int bs = wi >> 5, i = (wi >> 3) & 3, h = wi & 7;
;     const int kg = lane >> 4, li = lane & 15;
;     const int srow = bs * 4 + i;
;     const float* ACC1 = (const float*)(ws + O_ACC1); const float* rstd1 = (const float*)(ws + O_RSTD1);
;     float q[8];
;     { const float rq = rstd1[TP + srow] * (0.08838834764831845f * LOG2E);
;       const f32x4 q0 = acc1_4(ACC1, srow, 3072 + h * 128 + 8 * li), q1 = acc1_4(ACC1, srow, 3072 + h * 128 + 8 * li + 4);
;       q[0] = q0[0] * rq; q[1] = q0[1] * rq; q[2] = q0[2] * rq; q[3] = q0[3] * rq; q[4] = q1[0] * rq; q[5] = q1[1] * rq; q[6] = q1[2] * rq; q[7] = q1[3] * rq; }
;     if (kg == 0) {
;         const float rs = rstd1[TP + srow];
;         float* ko = p.out + OUT_KN + (size_t)srow * 1024 + h * 128 + 8 * li; float* vo = p.out + OUT_VN + (size_t)srow * 1024 + h * 128 + 8 * li;
;         *(f32x4*)ko = acc1_4(ACC1, srow, 4096 + h * 128 + 8 * li) * rs; *(f32x4*)(ko + 4) = acc1_4(ACC1, srow, 4096 + h * 128 + 8 * li + 4) * rs;
;         *(f32x4*)vo = acc1_4(ACC1, srow, 5120 + h * 128 + 8 * li) * rs; *(f32x4*)(vo + 4) = acc1_4(ACC1, srow, 5120 + h * 128 + 8 * li + 4) * rs;
; __global__ void __launch_bounds__(NTHR) fwd_megakernel(P p) {
;     ...
;         { const int t0 = fresh_tid(); const int w = __builtin_amdgcn_readfirstlane(t0 >> 6);
;           __syncthreads();
;           if (w < 4) { for (int wi = w * G + blockIdx.x; wi < 1024; wi += G * 4) attn_sample_item(p, wi, t0 & 63); }
.LBB0_453:
	s_andn2_b64 vcc, exec, s[0:1]
	s_cbranch_vccnz .LBB0_479
	s_mul_i32 s0, s3, s34
	s_add_i32 s3, s0, s2
	s_cmpk_gt_i32 s3, 0x3ff
	s_cbranch_scc1 .LBB0_479
	s_lshl_b32 s77, s34, 2
	s_add_u32 s26, s68, 0x6200000
	s_addc_u32 s27, s69, 0
	s_add_u32 s28, s68, 0x6280000
	s_addc_u32 s29, s69, 0
	s_add_u32 s30, s70, 0x183a6400
	s_addc_u32 s31, s71, 0
	s_cmpk_lg_i32 s34, 0x100
	s_cbranch_scc1 .Las_item
	s_lshr_b32 s14, s3, 8
	s_lshl_b32 s14, s14, 3
	s_and_b32 s15, s2, 7
	s_or_b32 s14, s14, s15
	s_lshr_b32 s15, s2, 3
	s_lshl_b32 s15, s15, 5
	s_or_b32 s3, s14, s15
.Las_item:
	s_ashr_i32 s14, s3, 5
	s_bfe_u32 s15, s3, 0x20003
	s_and_b32 s16, s3, 7
	s_lshl_b32 s17, s14, 2
	s_or_b32 s17, s17, s15
	s_lshl_b32 s18, s14, 23
	s_add_u32 s20, s56, s18
	s_addc_u32 s21, s57, 0
	s_add_u32 s24, s58, s18
	s_addc_u32 s25, s59, 0
	s_lshl_b32 s18, s17, 2
	s_add_u32 s18, s18, 0x8000
	s_load_dword s19, s[10:11], s18
	s_lshl_b32 s23, s16, 9
	v_and_b32_e32 v72, 15, v230
	v_lshlrev_b32_e32 v72, 4, v72
	v_bfe_u32 v73, v230, 4, 2
	v_cvt_f32_u32_e32 v202, v73
	v_add_u32_e32 v72, s23, v72
	s_add_u32 s43, s15, 0x800
	s_lshl_b32 s43, s43, 12
	v_add_u32_e32 v203, s43, v72
	s_sub_u32 s43, 0x7a, s16
	s_lshl_b32 s43, s43, 23
	v_mov_b32_e32 v201, s43
	v_mul_f32_e32 v201, 0xbfb8aa3b, v201
	s_mul_i32 s43, s17, 0x6000
	s_add_u32 s43, s43, 0x3000
	v_add_u32_e32 v64, s43, v72
	v_sub_u32_e32 v67, s15, v73
	v_max_i32_e32 v67, 0, v67
	v_lshl_add_u32 v67, s14, 2, v67
	v_lshlrev_b32_e32 v66, 2, v67
	v_add_u32_e32 v66, 0x8000, v66
	v_mul_u32_u24_e32 v65, 0x6000, v67
	v_add_u32_e32 v65, 0x4000, v65
	v_add_u32_e32 v65, v65, v72
	v_lshlrev_b32_e32 v68, 12, v73
	v_sub_u32_e32 v68, v203, v68
	s_mov_b32 s43, 0x7ff000
	v_add_u32_e32 v69, s43, v72
	v_min_u32_e32 v68, v68, v69
	v_add_u32_e32 v69, 0xfff80000, v203
	global_load_dword v70, v66, s[10:11]
	global_load_dwordx4 v[128:131], v68, s[20:21]
	global_load_dwordx4 v[132:135], v68, s[20:21] offset:256
	global_load_dwordx4 v[136:139], v68, s[24:25]
	global_load_dwordx4 v[140:143], v68, s[24:25] offset:256
	global_load_dwordx4 v[144:147], v69, s[20:21]
	global_load_dwordx4 v[148:151], v69, s[20:21] offset:256
	global_load_dwordx4 v[152:155], v69, s[24:25]
	global_load_dwordx4 v[156:159], v69, s[24:25] offset:256
	v_mov_b32_e32 v71, v64
	global_load_dwordx4 v[0:3], v71, s[8:9]
	v_add_u32_e32 v71, 0x300000, v71
	global_load_dwordx4 v[4:7], v71, s[8:9]
	v_add_u32_e32 v71, 0x300000, v71
	global_load_dwordx4 v[8:11], v71, s[8:9]
	v_add_u32_e32 v71, 0x300000, v71
	global_load_dwordx4 v[12:15], v71, s[8:9]
	v_add_u32_e32 v71, 0x300000, v71
	global_load_dwordx4 v[16:19], v71, s[8:9]
	v_add_u32_e32 v71, 0x300000, v71
	global_load_dwordx4 v[20:23], v71, s[8:9]
	v_add_u32_e32 v71, 0x300000, v71
	global_load_dwordx4 v[24:27], v71, s[8:9]
	v_add_u32_e32 v71, 0x300000, v71
	global_load_dwordx4 v[28:31], v71, s[8:9]
	v_mov_b32_e32 v71, v64
	global_load_dwordx4 v[32:35], v71, s[8:9] offset:256
	v_add_u32_e32 v71, 0x300000, v71
	global_load_dwordx4 v[36:39], v71, s[8:9] offset:256
	v_add_u32_e32 v71, 0x300000, v71
	global_load_dwordx4 v[40:43], v71, s[8:9] offset:256
	v_add_u32_e32 v71, 0x300000, v71
	global_load_dwordx4 v[44:47], v71, s[8:9] offset:256
	v_add_u32_e32 v71, 0x300000, v71
	global_load_dwordx4 v[48:51], v71, s[8:9] offset:256
	v_add_u32_e32 v71, 0x300000, v71
	global_load_dwordx4 v[52:55], v71, s[8:9] offset:256
	v_add_u32_e32 v71, 0x300000, v71
	global_load_dwordx4 v[56:59], v71, s[8:9] offset:256
	v_add_u32_e32 v71, 0x300000, v71
	global_load_dwordx4 v[60:63], v71, s[8:9] offset:256
	s_waitcnt vmcnt(8)
	v_add_f32_e32 v160, v0, v4
	v_add_f32_e32 v161, v1, v5
	v_add_f32_e32 v162, v2, v6
	v_add_f32_e32 v163, v3, v7
	v_add_f32_e32 v160, v160, v8
	v_add_f32_e32 v161, v161, v9
	v_add_f32_e32 v162, v162, v10
	v_add_f32_e32 v163, v163, v11
	v_add_f32_e32 v160, v160, v12
	v_add_f32_e32 v161, v161, v13
	v_add_f32_e32 v162, v162, v14
	v_add_f32_e32 v163, v163, v15
	v_add_f32_e32 v160, v160, v16
	v_add_f32_e32 v161, v161, v17
	v_add_f32_e32 v162, v162, v18
	v_add_f32_e32 v163, v163, v19
	v_add_f32_e32 v160, v160, v20
	v_add_f32_e32 v161, v161, v21
	v_add_f32_e32 v162, v162, v22
	v_add_f32_e32 v163, v163, v23
	v_add_f32_e32 v160, v160, v24
	v_add_f32_e32 v161, v161, v25
	v_add_f32_e32 v162, v162, v26
	v_add_f32_e32 v163, v163, v27
	v_add_f32_e32 v160, v160, v28
	v_add_f32_e32 v161, v161, v29
	v_add_f32_e32 v162, v162, v30
	v_add_f32_e32 v163, v163, v31
	v_mov_b32_e32 v71, v65
	global_load_dwordx4 v[0:3], v71, s[8:9]
	v_add_u32_e32 v71, 0x300000, v71
	global_load_dwordx4 v[4:7], v71, s[8:9]
	v_add_u32_e32 v71, 0x300000, v71
	global_load_dwordx4 v[8:11], v71, s[8:9]
	v_add_u32_e32 v71, 0x300000, v71
	global_load_dwordx4 v[12:15], v71, s[8:9]
	v_add_u32_e32 v71, 0x300000, v71
	global_load_dwordx4 v[16:19], v71, s[8:9]
	v_add_u32_e32 v71, 0x300000, v71
	global_load_dwordx4 v[20:23], v71, s[8:9]
	v_add_u32_e32 v71, 0x300000, v71
	global_load_dwordx4 v[24:27], v71, s[8:9]
	v_add_u32_e32 v71, 0x300000, v71
	global_load_dwordx4 v[28:31], v71, s[8:9]
	s_waitcnt vmcnt(8)
; __device__ __forceinline__ f32x4 acc1_4(const float* ACC1, int srow, int col) {
;     f32x4 s = *(const f32x4*)(ACC1 + (size_t)srow * N1 + col);
; #pragma unroll
;     for (int kp = 1; kp < 8; ++kp) s += *(const f32x4*)(ACC1 + ((size_t)kp * TS + srow) * N1 + col);
;     return s;
; }
; __device__ __forceinline__ void attn_sample_item(const P& p, int wi, int lane) {
;     ...
;         *(f32x4*)ko = acc1_4(ACC1, srow, 4096 + h * 128 + 8 * li) * rs; *(f32x4*)(ko + 4) = acc1_4(ACC1, srow, 4096 + h * 128 + 8 * li + 4) * rs;
;         *(f32x4*)vo = acc1_4(ACC1, srow, 5120 + h * 128 + 8 * li) * rs; *(f32x4*)(vo + 4) = acc1_4(ACC1, srow, 5120 + h * 128 + 8 * li + 4) * rs;
;     ...
;             else { const int nr = bs * 4 + (idx - 2048); const float rsn = rstd1[TP + nr]; const int c0 = 4096 + h * 128 + 8 * li;
;                 k0 = acc1_4(ACC1, nr, c0) * rsn; k1 = acc1_4(ACC1, nr, c0 + 4) * rsn; v0 = acc1_4(ACC1, nr, c0 + 1024) * rsn; v1 = acc1_4(ACC1, nr, c0 + 1028) * rsn; }
	v_add_f32_e32 v164, v32, v36
	v_add_f32_e32 v165, v33, v37
	v_add_f32_e32 v166, v34, v38
	v_add_f32_e32 v167, v35, v39
	v_add_f32_e32 v164, v164, v40
	v_add_f32_e32 v165, v165, v41
	v_add_f32_e32 v166, v166, v42
	v_add_f32_e32 v167, v167, v43
	v_add_f32_e32 v164, v164, v44
	v_add_f32_e32 v165, v165, v45
	v_add_f32_e32 v166, v166, v46
	v_add_f32_e32 v167, v167, v47
	v_add_f32_e32 v164, v164, v48
	v_add_f32_e32 v165, v165, v49
	v_add_f32_e32 v166, v166, v50
	v_add_f32_e32 v167, v167, v51
	v_add_f32_e32 v164, v164, v52
	v_add_f32_e32 v165, v165, v53
	v_add_f32_e32 v166, v166, v54
	v_add_f32_e32 v167, v167, v55
	v_add_f32_e32 v164, v164, v56
	v_add_f32_e32 v165, v165, v57
	v_add_f32_e32 v166, v166, v58
	v_add_f32_e32 v167, v167, v59
	v_add_f32_e32 v164, v164, v60
	v_add_f32_e32 v165, v165, v61
	v_add_f32_e32 v166, v166, v62
	v_add_f32_e32 v167, v167, v63
	v_mov_b32_e32 v71, v65
	global_load_dwordx4 v[32:35], v71, s[8:9] offset:256
	v_add_u32_e32 v71, 0x300000, v71
	global_load_dwordx4 v[36:39], v71, s[8:9] offset:256
	v_add_u32_e32 v71, 0x300000, v71
	global_load_dwordx4 v[40:43], v71, s[8:9] offset:256
	v_add_u32_e32 v71, 0x300000, v71
	global_load_dwordx4 v[44:47], v71, s[8:9] offset:256
	v_add_u32_e32 v71, 0x300000, v71
	global_load_dwordx4 v[48:51], v71, s[8:9] offset:256
	v_add_u32_e32 v71, 0x300000, v71
	global_load_dwordx4 v[52:55], v71, s[8:9] offset:256
	v_add_u32_e32 v71, 0x300000, v71
	global_load_dwordx4 v[56:59], v71, s[8:9] offset:256
	v_add_u32_e32 v71, 0x300000, v71
	global_load_dwordx4 v[60:63], v71, s[8:9] offset:256
	s_waitcnt vmcnt(8)
	v_add_f32_e32 v176, v0, v4
	v_add_f32_e32 v177, v1, v5
	v_add_f32_e32 v178, v2, v6
	v_add_f32_e32 v179, v3, v7
	v_add_f32_e32 v176, v176, v8
	v_add_f32_e32 v177, v177, v9
	v_add_f32_e32 v178, v178, v10
	v_add_f32_e32 v179, v179, v11
	v_add_f32_e32 v176, v176, v12
	v_add_f32_e32 v177, v177, v13
	v_add_f32_e32 v178, v178, v14
	v_add_f32_e32 v179, v179, v15
	v_add_f32_e32 v176, v176, v16
	v_add_f32_e32 v177, v177, v17
	v_add_f32_e32 v178, v178, v18
	v_add_f32_e32 v179, v179, v19
	v_add_f32_e32 v176, v176, v20
	v_add_f32_e32 v177, v177, v21
	v_add_f32_e32 v178, v178, v22
	v_add_f32_e32 v179, v179, v23
	v_add_f32_e32 v176, v176, v24
	v_add_f32_e32 v177, v177, v25
	v_add_f32_e32 v178, v178, v26
	v_add_f32_e32 v179, v179, v27
	v_add_f32_e32 v176, v176, v28
	v_add_f32_e32 v177, v177, v29
	v_add_f32_e32 v178, v178, v30
	v_add_f32_e32 v179, v179, v31
	v_add_u32_e32 v71, 0x1000, v65
	global_load_dwordx4 v[0:3], v71, s[8:9]
	v_add_u32_e32 v71, 0x300000, v71
	global_load_dwordx4 v[4:7], v71, s[8:9]
	v_add_u32_e32 v71, 0x300000, v71
	global_load_dwordx4 v[8:11], v71, s[8:9]
	v_add_u32_e32 v71, 0x300000, v71
	global_load_dwordx4 v[12:15], v71, s[8:9]
	v_add_u32_e32 v71, 0x300000, v71
	global_load_dwordx4 v[16:19], v71, s[8:9]
	v_add_u32_e32 v71, 0x300000, v71
	global_load_dwordx4 v[20:23], v71, s[8:9]
	v_add_u32_e32 v71, 0x300000, v71
	global_load_dwordx4 v[24:27], v71, s[8:9]
	v_add_u32_e32 v71, 0x300000, v71
	global_load_dwordx4 v[28:31], v71, s[8:9]
	s_waitcnt vmcnt(8)
	v_add_f32_e32 v180, v32, v36
	v_add_f32_e32 v181, v33, v37
	v_add_f32_e32 v182, v34, v38
	v_add_f32_e32 v183, v35, v39
	v_add_f32_e32 v180, v180, v40
	v_add_f32_e32 v181, v181, v41
	v_add_f32_e32 v182, v182, v42
	v_add_f32_e32 v183, v183, v43
	v_add_f32_e32 v180, v180, v44
	v_add_f32_e32 v181, v181, v45
	v_add_f32_e32 v182, v182, v46
	v_add_f32_e32 v183, v183, v47
	v_add_f32_e32 v180, v180, v48
	v_add_f32_e32 v181, v181, v49
	v_add_f32_e32 v182, v182, v50
	v_add_f32_e32 v183, v183, v51
	v_add_f32_e32 v180, v180, v52
	v_add_f32_e32 v181, v181, v53
	v_add_f32_e32 v182, v182, v54
	v_add_f32_e32 v183, v183, v55
	v_add_f32_e32 v180, v180, v56
	v_add_f32_e32 v181, v181, v57
	v_add_f32_e32 v182, v182, v58
	v_add_f32_e32 v183, v183, v59
	v_add_f32_e32 v180, v180, v60
	v_add_f32_e32 v181, v181, v61
	v_add_f32_e32 v182, v182, v62
	v_add_f32_e32 v183, v183, v63
	v_add_u32_e32 v71, 0x1000, v65
	global_load_dwordx4 v[32:35], v71, s[8:9] offset:256
	v_add_u32_e32 v71, 0x300000, v71
	global_load_dwordx4 v[36:39], v71, s[8:9] offset:256
	v_add_u32_e32 v71, 0x300000, v71
	global_load_dwordx4 v[40:43], v71, s[8:9] offset:256
	v_add_u32_e32 v71, 0x300000, v71
	global_load_dwordx4 v[44:47], v71, s[8:9] offset:256
	v_add_u32_e32 v71, 0x300000, v71
	global_load_dwordx4 v[48:51], v71, s[8:9] offset:256
	v_add_u32_e32 v71, 0x300000, v71
	global_load_dwordx4 v[52:55], v71, s[8:9] offset:256
	v_add_u32_e32 v71, 0x300000, v71
	global_load_dwordx4 v[56:59], v71, s[8:9] offset:256
	v_add_u32_e32 v71, 0x300000, v71
	global_load_dwordx4 v[60:63], v71, s[8:9] offset:256
	s_waitcnt vmcnt(8)
	v_add_f32_e32 v184, v0, v4
	v_add_f32_e32 v185, v1, v5
	v_add_f32_e32 v186, v2, v6
	v_add_f32_e32 v187, v3, v7
	v_add_f32_e32 v184, v184, v8
	v_add_f32_e32 v185, v185, v9
	v_add_f32_e32 v186, v186, v10
	v_add_f32_e32 v187, v187, v11
	v_add_f32_e32 v184, v184, v12
	v_add_f32_e32 v185, v185, v13
	v_add_f32_e32 v186, v186, v14
	v_add_f32_e32 v187, v187, v15
	v_add_f32_e32 v184, v184, v16
	v_add_f32_e32 v185, v185, v17
	v_add_f32_e32 v186, v186, v18
	v_add_f32_e32 v187, v187, v19
	v_add_f32_e32 v184, v184, v20
	v_add_f32_e32 v185, v185, v21
	v_add_f32_e32 v186, v186, v22
	v_add_f32_e32 v187, v187, v23
	v_add_f32_e32 v184, v184, v24
	v_add_f32_e32 v185, v185, v25
	v_add_f32_e32 v186, v186, v26
	v_add_f32_e32 v187, v187, v27
	v_add_f32_e32 v184, v184, v28
	v_add_f32_e32 v185, v185, v29
	v_add_f32_e32 v186, v186, v30
	v_add_f32_e32 v187, v187, v31
	s_waitcnt vmcnt(0)
; __device__ __forceinline__ void attn_sample_item(const P& p, int wi, int lane) {
;     ...
;         const float rs = rstd1[TP + srow];
;         float* ko = p.out + OUT_KN + (size_t)srow * 1024 + h * 128 + 8 * li; float* vo = p.out + OUT_VN + (size_t)srow * 1024 + h * 128 + 8 * li;
;         *(f32x4*)ko = acc1_4(ACC1, srow, 4096 + h * 128 + 8 * li) * rs; *(f32x4*)(ko + 4) = acc1_4(ACC1, srow, 4096 + h * 128 + 8 * li + 4) * rs;
;         *(f32x4*)vo = acc1_4(ACC1, srow, 5120 + h * 128 + 8 * li) * rs; *(f32x4*)(vo + 4) = acc1_4(ACC1, srow, 5120 + h * 128 + 8 * li + 4) * rs;
;     ...
;             if (idx < 2048) { const size_t off = (((size_t)bs * 2048 + idx) * 8 + h) * 128 + 8 * li;
;                 k0 = __builtin_nontemporal_load((const f32x4*)(p.cache_k + off)); k1 = __builtin_nontemporal_load((const f32x4*)(p.cache_k + off + 4)); v0 = __builtin_nontemporal_load((const f32x4*)(p.cache_v + off)); v1 = __builtin_nontemporal_load((const f32x4*)(p.cache_v + off + 4)); }
;             else { const int nr = bs * 4 + (idx - 2048); const float rsn = rstd1[TP + nr]; const int c0 = 4096 + h * 128 + 8 * li;
;                 k0 = acc1_4(ACC1, nr, c0) * rsn; k1 = acc1_4(ACC1, nr, c0 + 4) * rsn; v0 = acc1_4(ACC1, nr, c0 + 1024) * rsn; v1 = acc1_4(ACC1, nr, c0 + 1028) * rsn; }
	v_add_f32_e32 v188, v32, v36
	v_add_f32_e32 v189, v33, v37
	v_add_f32_e32 v190, v34, v38
	v_add_f32_e32 v191, v35, v39
	v_add_f32_e32 v188, v188, v40
	v_add_f32_e32 v189, v189, v41
	v_add_f32_e32 v190, v190, v42
	v_add_f32_e32 v191, v191, v43
	v_add_f32_e32 v188, v188, v44
	v_add_f32_e32 v189, v189, v45
	v_add_f32_e32 v190, v190, v46
	v_add_f32_e32 v191, v191, v47
	v_add_f32_e32 v188, v188, v48
	v_add_f32_e32 v189, v189, v49
	v_add_f32_e32 v190, v190, v50
	v_add_f32_e32 v191, v191, v51
	v_add_f32_e32 v188, v188, v52
	v_add_f32_e32 v189, v189, v53
	v_add_f32_e32 v190, v190, v54
	v_add_f32_e32 v191, v191, v55
	v_add_f32_e32 v188, v188, v56
	v_add_f32_e32 v189, v189, v57
	v_add_f32_e32 v190, v190, v58
	v_add_f32_e32 v191, v191, v59
	v_add_f32_e32 v188, v188, v60
	v_add_f32_e32 v189, v189, v61
	v_add_f32_e32 v190, v190, v62
	v_add_f32_e32 v191, v191, v63
	s_waitcnt lgkmcnt(0)
	v_mov_b32_e32 v71, s19
	v_mul_f32_e32 v71, 0x3e0293ee, v71
	v_mul_f32_e32 v160, v160, v71
	v_mul_f32_e32 v161, v161, v71
	v_mul_f32_e32 v162, v162, v71
	v_mul_f32_e32 v163, v163, v71
	v_mul_f32_e32 v164, v164, v71
	v_mul_f32_e32 v165, v165, v71
	v_mul_f32_e32 v166, v166, v71
	v_mul_f32_e32 v167, v167, v71
	v_mul_f32_e32 v176, v176, v70
	v_mul_f32_e32 v177, v177, v70
	v_mul_f32_e32 v178, v178, v70
	v_mul_f32_e32 v179, v179, v70
	v_mul_f32_e32 v180, v180, v70
	v_mul_f32_e32 v181, v181, v70
	v_mul_f32_e32 v182, v182, v70
	v_mul_f32_e32 v183, v183, v70
	v_mul_f32_e32 v184, v184, v70
	v_mul_f32_e32 v185, v185, v70
	v_mul_f32_e32 v186, v186, v70
	v_mul_f32_e32 v187, v187, v70
	v_mul_f32_e32 v188, v188, v70
	v_mul_f32_e32 v189, v189, v70
	v_mul_f32_e32 v190, v190, v70
	v_mul_f32_e32 v191, v191, v70
	s_lshl_b32 s43, s17, 12
	v_add_u32_e32 v71, s43, v72
	s_mov_b64 exec, 0xffff
	global_store_dwordx4 v71, v[176:179], s[26:27]
	global_store_dwordx4 v71, v[180:183], s[26:27] offset:256
	global_store_dwordx4 v71, v[184:187], s[28:29]
	global_store_dwordx4 v71, v[188:191], s[28:29] offset:256
	s_mov_b64 exec, -1
	v_cmp_ge_u32_e32 vcc, s15, v73
	s_nop 1
	v_cndmask_b32_e32 v128, v128, v176, vcc
	v_cndmask_b32_e32 v129, v129, v177, vcc
	v_cndmask_b32_e32 v130, v130, v178, vcc
	v_cndmask_b32_e32 v131, v131, v179, vcc
	v_cndmask_b32_e32 v132, v132, v180, vcc
	v_cndmask_b32_e32 v133, v133, v181, vcc
	v_cndmask_b32_e32 v134, v134, v182, vcc
	v_cndmask_b32_e32 v135, v135, v183, vcc
	v_cndmask_b32_e32 v136, v136, v184, vcc
	v_cndmask_b32_e32 v137, v137, v185, vcc
	v_cndmask_b32_e32 v138, v138, v186, vcc
	v_cndmask_b32_e32 v139, v139, v187, vcc
	v_cndmask_b32_e32 v140, v140, v188, vcc
	v_cndmask_b32_e32 v141, v141, v189, vcc
	v_cndmask_b32_e32 v142, v142, v190, vcc
	v_cndmask_b32_e32 v143, v143, v191, vcc
	v_bfe_u32 v183, v230, 4, 2
	v_lshlrev_b32_e32 v195, 12, v183
	v_sub_u32_e32 v195, v203, v195
	s_mov_b32 s42, 0xffffc000
	v_add_u32_e32 v195, s42, v195
	global_load_dwordx4 v[16:19], v195, s[20:21]
	global_load_dwordx4 v[20:23], v195, s[20:21] offset:256
	global_load_dwordx4 v[24:27], v195, s[24:25]
	global_load_dwordx4 v[28:31], v195, s[24:25] offset:256
	v_add_u32_e32 v195, s42, v195
	global_load_dwordx4 v[32:35], v195, s[20:21]
	global_load_dwordx4 v[36:39], v195, s[20:21] offset:256
	global_load_dwordx4 v[40:43], v195, s[24:25]
	global_load_dwordx4 v[44:47], v195, s[24:25] offset:256
	v_add_u32_e32 v195, s42, v195
	global_load_dwordx4 v[48:51], v195, s[20:21]
	global_load_dwordx4 v[52:55], v195, s[20:21] offset:256
	global_load_dwordx4 v[56:59], v195, s[24:25]
	global_load_dwordx4 v[60:63], v195, s[24:25] offset:256
	v_add_u32_e32 v195, s42, v195
	global_load_dwordx4 v[64:67], v195, s[20:21]
	global_load_dwordx4 v[68:71], v195, s[20:21] offset:256
	global_load_dwordx4 v[72:75], v195, s[24:25]
	global_load_dwordx4 v[76:79], v195, s[24:25] offset:256
	v_add_u32_e32 v195, s42, v195
	global_load_dwordx4 v[80:83], v195, s[20:21]
	global_load_dwordx4 v[84:87], v195, s[20:21] offset:256
	global_load_dwordx4 v[88:91], v195, s[24:25]
	global_load_dwordx4 v[92:95], v195, s[24:25] offset:256
	v_add_u32_e32 v195, s42, v195
	global_load_dwordx4 v[96:99], v195, s[20:21]
	global_load_dwordx4 v[100:103], v195, s[20:21] offset:256
	global_load_dwordx4 v[104:107], v195, s[24:25]
; __device__ __forceinline__ float fexp2(float x) { return __builtin_amdgcn_exp2f(x); }
; __device__ __forceinline__ void attn_sample_item(const P& p, int wi, int lane) {
;     ...
;     float m = -1e30f, l = 0.f, acc[8];
; #pragma unroll
;     for (int e = 0; e < 8; ++e) acc[e] = 0.f;
;     const float sl = fexp2(-(float)(h + 1)) * LOG2E;
;     for (int g = 0; g < 3; ++g) {
;         const int d = 1 << (2 * g);
; #pragma unroll 3
;         for (int jj = 0; jj < 33; ++jj) {
;             const int j = 4 * jj + kg; const bool valid = j <= 128; const int jc = valid ? j : 128;
;             const int idx = 2048 + i - d * jc;
;             f32x4 k0, k1, v0, v1;
;             if (idx < 2048) { const size_t off = (((size_t)bs * 2048 + idx) * 8 + h) * 128 + 8 * li;
;                 k0 = __builtin_nontemporal_load((const f32x4*)(p.cache_k + off)); k1 = __builtin_nontemporal_load((const f32x4*)(p.cache_k + off + 4)); v0 = __builtin_nontemporal_load((const f32x4*)(p.cache_v + off)); v1 = __builtin_nontemporal_load((const f32x4*)(p.cache_v + off + 4)); }
;             else { const int nr = bs * 4 + (idx - 2048); const float rsn = rstd1[TP + nr]; const int c0 = 4096 + h * 128 + 8 * li;
;                 k0 = acc1_4(ACC1, nr, c0) * rsn; k1 = acc1_4(ACC1, nr, c0 + 4) * rsn; v0 = acc1_4(ACC1, nr, c0 + 1024) * rsn; v1 = acc1_4(ACC1, nr, c0 + 1028) * rsn; }
;             float dot = (q[0] * k0[0] + q[1] * k0[1]) + (q[2] * k0[2] + q[3] * k0[3]) + (q[4] * k1[0] + q[5] * k1[1]) + (q[6] * k1[2] + q[7] * k1[3]);
;             dot += __shfl_xor(dot, 1); dot += __shfl_xor(dot, 2); dot += __shfl_xor(dot, 4); dot += __shfl_xor(dot, 8);
;             const float s = valid ? dot - sl * (float)(d * j) : -INFINITY;
;             const float mn = fmaxf(m, s), sc = fexp2(m - mn), pe = fexp2(s - mn);
;             l = l * sc + pe;
;             acc[0] = acc[0] * sc + pe * v0[0]; acc[1] = acc[1] * sc + pe * v0[1]; acc[2] = acc[2] * sc + pe * v0[2]; acc[3] = acc[3] * sc + pe * v0[3];
;             acc[4] = acc[4] * sc + pe * v1[0]; acc[5] = acc[5] * sc + pe * v1[1]; acc[6] = acc[6] * sc + pe * v1[2]; acc[7] = acc[7] * sc + pe * v1[3];
;             m = mn;
	global_load_dwordx4 v[108:111], v195, s[24:25] offset:256
	v_add_u32_e32 v195, s42, v195
	global_load_dwordx4 v[112:115], v195, s[20:21]
	global_load_dwordx4 v[116:119], v195, s[20:21] offset:256
	global_load_dwordx4 v[120:123], v195, s[24:25]
	global_load_dwordx4 v[124:127], v195, s[24:25] offset:256
	v_add_u32_e32 v195, s42, v195
	global_load_dwordx4 v[0:3], v195, s[20:21]
	global_load_dwordx4 v[4:7], v195, s[20:21] offset:256
	global_load_dwordx4 v[8:11], v195, s[24:25]
	global_load_dwordx4 v[12:15], v195, s[24:25] offset:256
	v_lshlrev_b32_e32 v176, 14, v183
	v_sub_u32_e32 v176, v203, v176
	v_add_u32_e32 v176, 0xc000, v176
	v_lshlrev_b32_e32 v177, 16, v183
	v_sub_u32_e32 v177, v203, v177
	v_add_u32_e32 v177, 0x30000, v177
	v_add_f32_e32 v182, 1.0, v202
	v_mul_f32_e32 v182, v182, v201
	v_mul_f32_e32 v178, 4.0, v182
	v_mul_f32_e32 v179, 16.0, v182
	v_mul_f32_e32 v180, 16.0, v201
	v_mul_f32_e32 v181, 64.0, v201
	v_mul_f32_e32 v196, 4.0, v201
	v_mov_b32_e32 v192, 0xf149f2ca
	v_mov_b32_e32 v193, 0
	v_mov_b32_e32 v168, 0
	v_mov_b32_e32 v169, 0
	v_mov_b32_e32 v170, 0
	v_mov_b32_e32 v171, 0
	v_mov_b32_e32 v172, 0
	v_mov_b32_e32 v173, 0
	v_mov_b32_e32 v174, 0
	v_mov_b32_e32 v175, 0
	v_mul_f32_e32 v194, v201, v202
	v_mov_b32_e32 v182, 0x3dcae00d
	v_cmp_eq_u32_e32 vcc, 0, v183
	s_nop 1
	v_cndmask_b32_e32 v194, v194, v182, vcc
	v_fma_f32 v197, v160, v128, v194
	v_fmac_f32_e32 v197, v161, v129
	v_fmac_f32_e32 v197, v162, v130
	v_fmac_f32_e32 v197, v163, v131
	v_fmac_f32_e32 v197, v164, v132
	v_fmac_f32_e32 v197, v165, v133
	v_fmac_f32_e32 v197, v166, v134
	v_fmac_f32_e32 v197, v167, v135
	s_nop 1
	v_add_f32_dpp v197, v197, v197 row_ror:8 row_mask:0xf bank_mask:0xf
	s_nop 1
	v_add_f32_dpp v197, v197, v197 row_ror:4 row_mask:0xf bank_mask:0xf
	s_nop 1
	v_add_f32_dpp v197, v197, v197 row_ror:2 row_mask:0xf bank_mask:0xf
	s_nop 1
	v_add_f32_dpp v197, v197, v197 row_ror:1 row_mask:0xf bank_mask:0xf
	v_max_f32_e32 v198, v192, v197
	v_sub_f32_e32 v199, v192, v198
	v_sub_f32_e32 v200, v197, v198
	v_exp_f32_e32 v199, v199
	v_exp_f32_e32 v200, v200
	v_mov_b32_e32 v192, v198
	v_fma_f32 v193, v193, v199, v200
	v_mul_f32_e32 v168, v168, v199
	v_mul_f32_e32 v169, v169, v199
	v_mul_f32_e32 v170, v170, v199
	v_mul_f32_e32 v171, v171, v199
	v_mul_f32_e32 v172, v172, v199
	v_mul_f32_e32 v173, v173, v199
	v_mul_f32_e32 v174, v174, v199
	v_mul_f32_e32 v175, v175, v199
	v_fmac_f32_e32 v168, v200, v136
	v_fmac_f32_e32 v169, v200, v137
	v_fmac_f32_e32 v170, v200, v138
	v_fmac_f32_e32 v171, v200, v139
	v_fmac_f32_e32 v172, v200, v140
	v_fmac_f32_e32 v173, v200, v141
	v_fmac_f32_e32 v174, v200, v142
	v_fmac_f32_e32 v175, v200, v143
	v_mul_f32_e32 v194, 0x43000000, v201
	v_mov_b32_e32 v182, 0xff800000
	v_cndmask_b32_e32 v194, v182, v194, vcc
	v_fma_f32 v197, v160, v144, v194
	v_fmac_f32_e32 v197, v161, v145
	v_fmac_f32_e32 v197, v162, v146
	v_fmac_f32_e32 v197, v163, v147
	v_fmac_f32_e32 v197, v164, v148
	v_fmac_f32_e32 v197, v165, v149
	v_fmac_f32_e32 v197, v166, v150
	v_fmac_f32_e32 v197, v167, v151
	s_nop 1
	v_add_f32_dpp v197, v197, v197 row_ror:8 row_mask:0xf bank_mask:0xf
	s_nop 1
	v_add_f32_dpp v197, v197, v197 row_ror:4 row_mask:0xf bank_mask:0xf
	s_nop 1
	v_add_f32_dpp v197, v197, v197 row_ror:2 row_mask:0xf bank_mask:0xf
	s_nop 1
	v_add_f32_dpp v197, v197, v197 row_ror:1 row_mask:0xf bank_mask:0xf
	v_max_f32_e32 v198, v192, v197
	v_sub_f32_e32 v199, v192, v198
	v_sub_f32_e32 v200, v197, v198
	v_exp_f32_e32 v199, v199
	v_exp_f32_e32 v200, v200
	v_mov_b32_e32 v192, v198
	v_fma_f32 v193, v193, v199, v200
	v_mul_f32_e32 v168, v168, v199
	v_mul_f32_e32 v169, v169, v199
	v_mul_f32_e32 v170, v170, v199
	v_mul_f32_e32 v171, v171, v199
	v_mul_f32_e32 v172, v172, v199
	v_mul_f32_e32 v173, v173, v199
	v_mul_f32_e32 v174, v174, v199
	v_mul_f32_e32 v175, v175, v199
	v_fmac_f32_e32 v168, v200, v152
	v_fmac_f32_e32 v169, v200, v153
	v_fmac_f32_e32 v170, v200, v154
	v_fmac_f32_e32 v171, v200, v155
	v_fmac_f32_e32 v172, v200, v156
	v_fmac_f32_e32 v173, v200, v157
	v_fmac_f32_e32 v174, v200, v158
	v_fmac_f32_e32 v175, v200, v159
	v_add_f32_e32 v194, 4.0, v202
	v_mul_f32_e32 v194, v194, v201
	s_mov_b32 s33, 0
	s_branch .Las_slot1

; __device__ __forceinline__ float fexp2(float x) { return __builtin_amdgcn_exp2f(x); }
; __device__ __forceinline__ void attn_sample_item(const P& p, int wi, int lane) {
;     ...
;         for (int jj = 0; jj < 33; ++jj) {
;             const int j = 4 * jj + kg; const bool valid = j <= 128; const int jc = valid ? j : 128;
;             const int idx = 2048 + i - d * jc;
;             f32x4 k0, k1, v0, v1;
;             if (idx < 2048) { const size_t off = (((size_t)bs * 2048 + idx) * 8 + h) * 128 + 8 * li;
;                 k0 = __builtin_nontemporal_load((const f32x4*)(p.cache_k + off)); k1 = __builtin_nontemporal_load((const f32x4*)(p.cache_k + off + 4)); v0 = __builtin_nontemporal_load((const f32x4*)(p.cache_v + off)); v1 = __builtin_nontemporal_load((const f32x4*)(p.cache_v + off + 4)); }
;             else { const int nr = bs * 4 + (idx - 2048); const float rsn = rstd1[TP + nr]; const int c0 = 4096 + h * 128 + 8 * li;
;                 k0 = acc1_4(ACC1, nr, c0) * rsn; k1 = acc1_4(ACC1, nr, c0 + 4) * rsn; v0 = acc1_4(ACC1, nr, c0 + 1024) * rsn; v1 = acc1_4(ACC1, nr, c0 + 1028) * rsn; }
;             float dot = (q[0] * k0[0] + q[1] * k0[1]) + (q[2] * k0[2] + q[3] * k0[3]) + (q[4] * k1[0] + q[5] * k1[1]) + (q[6] * k1[2] + q[7] * k1[3]);
;             dot += __shfl_xor(dot, 1); dot += __shfl_xor(dot, 2); dot += __shfl_xor(dot, 4); dot += __shfl_xor(dot, 8);
;             const float s = valid ? dot - sl * (float)(d * j) : -INFINITY;
;             const float mn = fmaxf(m, s), sc = fexp2(m - mn), pe = fexp2(s - mn);
;             l = l * sc + pe;
;             acc[0] = acc[0] * sc + pe * v0[0]; acc[1] = acc[1] * sc + pe * v0[1]; acc[2] = acc[2] * sc + pe * v0[2]; acc[3] = acc[3] * sc + pe * v0[3];
;             acc[4] = acc[4] * sc + pe * v1[0]; acc[5] = acc[5] * sc + pe * v1[1]; acc[6] = acc[6] * sc + pe * v1[2]; acc[7] = acc[7] * sc + pe * v1[3];
;             m = mn;
;         }
.Las_sw4:
	s_waitcnt vmcnt(28)
	v_fma_f32 v197, v160, v0, v194
	v_fmac_f32_e32 v197, v161, v1
	v_fmac_f32_e32 v197, v162, v2
	v_fmac_f32_e32 v197, v163, v3
	v_fmac_f32_e32 v197, v164, v4
	v_fmac_f32_e32 v197, v165, v5
	v_fmac_f32_e32 v197, v166, v6
	v_fmac_f32_e32 v197, v167, v7
	s_nop 1
	v_add_f32_dpp v197, v197, v197 row_ror:8 row_mask:0xf bank_mask:0xf
	s_nop 1
	v_add_f32_dpp v197, v197, v197 row_ror:4 row_mask:0xf bank_mask:0xf
	s_nop 1
	v_add_f32_dpp v197, v197, v197 row_ror:2 row_mask:0xf bank_mask:0xf
	s_nop 1
	v_add_f32_dpp v197, v197, v197 row_ror:1 row_mask:0xf bank_mask:0xf
	v_max_f32_e32 v198, v192, v197
	v_sub_f32_e32 v199, v192, v198
	v_sub_f32_e32 v200, v197, v198
	v_exp_f32_e32 v199, v199
	v_exp_f32_e32 v200, v200
	v_mov_b32_e32 v192, v198
	v_fma_f32 v193, v193, v199, v200
	v_mul_f32_e32 v168, v168, v199
	v_mul_f32_e32 v169, v169, v199
	v_mul_f32_e32 v170, v170, v199
	v_mul_f32_e32 v171, v171, v199
	v_mul_f32_e32 v172, v172, v199
	v_mul_f32_e32 v173, v173, v199
	v_mul_f32_e32 v174, v174, v199
	v_mul_f32_e32 v175, v175, v199
	v_fmac_f32_e32 v168, v200, v8
	v_fmac_f32_e32 v169, v200, v9
	v_fmac_f32_e32 v170, v200, v10
	v_fmac_f32_e32 v171, v200, v11
	v_fmac_f32_e32 v172, v200, v12
	v_fmac_f32_e32 v173, v200, v13
	v_fmac_f32_e32 v174, v200, v14
	v_fmac_f32_e32 v175, v200, v15
	v_add_f32_e32 v194, v194, v196
	v_add_u32_e32 v195, s42, v195
	global_load_dwordx4 v[0:3], v195, s[20:21]
	global_load_dwordx4 v[4:7], v195, s[20:21] offset:256
	global_load_dwordx4 v[8:11], v195, s[24:25]
	global_load_dwordx4 v[12:15], v195, s[24:25] offset:256
.Las_slot1:
	s_waitcnt vmcnt(28)
	v_fma_f32 v197, v160, v16, v194
	v_fmac_f32_e32 v197, v161, v17
	v_fmac_f32_e32 v197, v162, v18
	v_fmac_f32_e32 v197, v163, v19
	v_fmac_f32_e32 v197, v164, v20
	v_fmac_f32_e32 v197, v165, v21
	v_fmac_f32_e32 v197, v166, v22
	v_fmac_f32_e32 v197, v167, v23
	s_nop 1
	v_add_f32_dpp v197, v197, v197 row_ror:8 row_mask:0xf bank_mask:0xf
	s_nop 1
	v_add_f32_dpp v197, v197, v197 row_ror:4 row_mask:0xf bank_mask:0xf
	s_nop 1
	v_add_f32_dpp v197, v197, v197 row_ror:2 row_mask:0xf bank_mask:0xf
	s_nop 1
	v_add_f32_dpp v197, v197, v197 row_ror:1 row_mask:0xf bank_mask:0xf
	v_max_f32_e32 v198, v192, v197
	v_sub_f32_e32 v199, v192, v198
	v_sub_f32_e32 v200, v197, v198
	v_exp_f32_e32 v199, v199
	v_exp_f32_e32 v200, v200
	v_mov_b32_e32 v192, v198
	v_fma_f32 v193, v193, v199, v200
	v_mul_f32_e32 v168, v168, v199
	v_mul_f32_e32 v169, v169, v199
	v_mul_f32_e32 v170, v170, v199
	v_mul_f32_e32 v171, v171, v199
	v_mul_f32_e32 v172, v172, v199
	v_mul_f32_e32 v173, v173, v199
	v_mul_f32_e32 v174, v174, v199
	v_mul_f32_e32 v175, v175, v199
	v_fmac_f32_e32 v168, v200, v24
	v_fmac_f32_e32 v169, v200, v25
	v_fmac_f32_e32 v170, v200, v26
	v_fmac_f32_e32 v171, v200, v27
	v_fmac_f32_e32 v172, v200, v28
	v_fmac_f32_e32 v173, v200, v29
	v_fmac_f32_e32 v174, v200, v30
	v_fmac_f32_e32 v175, v200, v31
	v_add_f32_e32 v194, v194, v196
	v_add_u32_e32 v195, s42, v195
	global_load_dwordx4 v[16:19], v195, s[20:21]
	global_load_dwordx4 v[20:23], v195, s[20:21] offset:256
	global_load_dwordx4 v[24:27], v195, s[24:25]
	global_load_dwordx4 v[28:31], v195, s[24:25] offset:256
	s_waitcnt vmcnt(28)
	v_fma_f32 v197, v160, v32, v194
	v_fmac_f32_e32 v197, v161, v33
	v_fmac_f32_e32 v197, v162, v34
	v_fmac_f32_e32 v197, v163, v35
	v_fmac_f32_e32 v197, v164, v36
	v_fmac_f32_e32 v197, v165, v37
	v_fmac_f32_e32 v197, v166, v38
	v_fmac_f32_e32 v197, v167, v39
	s_nop 1
	v_add_f32_dpp v197, v197, v197 row_ror:8 row_mask:0xf bank_mask:0xf
	s_nop 1
	v_add_f32_dpp v197, v197, v197 row_ror:4 row_mask:0xf bank_mask:0xf
	s_nop 1
	v_add_f32_dpp v197, v197, v197 row_ror:2 row_mask:0xf bank_mask:0xf
	s_nop 1
	v_add_f32_dpp v197, v197, v197 row_ror:1 row_mask:0xf bank_mask:0xf
	v_max_f32_e32 v198, v192, v197
	v_sub_f32_e32 v199, v192, v198
	v_sub_f32_e32 v200, v197, v198
	v_exp_f32_e32 v199, v199
	v_exp_f32_e32 v200, v200
	v_mov_b32_e32 v192, v198
	v_fma_f32 v193, v193, v199, v200
	v_mul_f32_e32 v168, v168, v199
	v_mul_f32_e32 v169, v169, v199
	v_mul_f32_e32 v170, v170, v199
	v_mul_f32_e32 v171, v171, v199
	v_mul_f32_e32 v172, v172, v199
	v_mul_f32_e32 v173, v173, v199
	v_mul_f32_e32 v174, v174, v199
	v_mul_f32_e32 v175, v175, v199
	v_fmac_f32_e32 v168, v200, v40
	v_fmac_f32_e32 v169, v200, v41
	v_fmac_f32_e32 v170, v200, v42
	v_fmac_f32_e32 v171, v200, v43
	v_fmac_f32_e32 v172, v200, v44
	v_fmac_f32_e32 v173, v200, v45
	v_fmac_f32_e32 v174, v200, v46
	v_fmac_f32_e32 v175, v200, v47
	v_add_f32_e32 v194, v194, v196
	v_add_u32_e32 v195, s42, v195
	global_load_dwordx4 v[32:35], v195, s[20:21]
	global_load_dwordx4 v[36:39], v195, s[20:21] offset:256
	global_load_dwordx4 v[40:43], v195, s[24:25]
	global_load_dwordx4 v[44:47], v195, s[24:25] offset:256
	s_waitcnt vmcnt(28)
	v_fma_f32 v197, v160, v48, v194
	v_fmac_f32_e32 v197, v161, v49
	v_fmac_f32_e32 v197, v162, v50
	v_fmac_f32_e32 v197, v163, v51
	v_fmac_f32_e32 v197, v164, v52
	v_fmac_f32_e32 v197, v165, v53
	v_fmac_f32_e32 v197, v166, v54
	v_fmac_f32_e32 v197, v167, v55
	s_nop 1
	v_add_f32_dpp v197, v197, v197 row_ror:8 row_mask:0xf bank_mask:0xf
	s_nop 1
	v_add_f32_dpp v197, v197, v197 row_ror:4 row_mask:0xf bank_mask:0xf
	s_nop 1
	v_add_f32_dpp v197, v197, v197 row_ror:2 row_mask:0xf bank_mask:0xf
	s_nop 1
	v_add_f32_dpp v197, v197, v197 row_ror:1 row_mask:0xf bank_mask:0xf
	v_max_f32_e32 v198, v192, v197
	v_sub_f32_e32 v199, v192, v198
	v_sub_f32_e32 v200, v197, v198
	v_exp_f32_e32 v199, v199
	v_exp_f32_e32 v200, v200
	v_mov_b32_e32 v192, v198
	v_fma_f32 v193, v193, v199, v200
	v_mul_f32_e32 v168, v168, v199
	v_mul_f32_e32 v169, v169, v199
	v_mul_f32_e32 v170, v170, v199
	v_mul_f32_e32 v171, v171, v199
	v_mul_f32_e32 v172, v172, v199
	v_mul_f32_e32 v173, v173, v199
	v_mul_f32_e32 v174, v174, v199
	v_mul_f32_e32 v175, v175, v199
	v_fmac_f32_e32 v168, v200, v56
	v_fmac_f32_e32 v169, v200, v57
	v_fmac_f32_e32 v170, v200, v58
	v_fmac_f32_e32 v171, v200, v59
	v_fmac_f32_e32 v172, v200, v60
	v_fmac_f32_e32 v173, v200, v61
	v_fmac_f32_e32 v174, v200, v62
	v_fmac_f32_e32 v175, v200, v63
	v_add_f32_e32 v194, v194, v196
	v_add_u32_e32 v195, s42, v195
	global_load_dwordx4 v[48:51], v195, s[20:21]
	global_load_dwordx4 v[52:55], v195, s[20:21] offset:256
	global_load_dwordx4 v[56:59], v195, s[24:25]
	global_load_dwordx4 v[60:63], v195, s[24:25] offset:256
	s_waitcnt vmcnt(28)
; __device__ __forceinline__ float fexp2(float x) { return __builtin_amdgcn_exp2f(x); }
; __device__ __forceinline__ void attn_sample_item(const P& p, int wi, int lane) {
;     ...
;         for (int jj = 0; jj < 33; ++jj) {
;             const int j = 4 * jj + kg; const bool valid = j <= 128; const int jc = valid ? j : 128;
;             const int idx = 2048 + i - d * jc;
;             f32x4 k0, k1, v0, v1;
;             if (idx < 2048) { const size_t off = (((size_t)bs * 2048 + idx) * 8 + h) * 128 + 8 * li;
;                 k0 = __builtin_nontemporal_load((const f32x4*)(p.cache_k + off)); k1 = __builtin_nontemporal_load((const f32x4*)(p.cache_k + off + 4)); v0 = __builtin_nontemporal_load((const f32x4*)(p.cache_v + off)); v1 = __builtin_nontemporal_load((const f32x4*)(p.cache_v + off + 4)); }
;             else { const int nr = bs * 4 + (idx - 2048); const float rsn = rstd1[TP + nr]; const int c0 = 4096 + h * 128 + 8 * li;
;                 k0 = acc1_4(ACC1, nr, c0) * rsn; k1 = acc1_4(ACC1, nr, c0 + 4) * rsn; v0 = acc1_4(ACC1, nr, c0 + 1024) * rsn; v1 = acc1_4(ACC1, nr, c0 + 1028) * rsn; }
;             float dot = (q[0] * k0[0] + q[1] * k0[1]) + (q[2] * k0[2] + q[3] * k0[3]) + (q[4] * k1[0] + q[5] * k1[1]) + (q[6] * k1[2] + q[7] * k1[3]);
;             dot += __shfl_xor(dot, 1); dot += __shfl_xor(dot, 2); dot += __shfl_xor(dot, 4); dot += __shfl_xor(dot, 8);
;             const float s = valid ? dot - sl * (float)(d * j) : -INFINITY;
;             const float mn = fmaxf(m, s), sc = fexp2(m - mn), pe = fexp2(s - mn);
;             l = l * sc + pe;
;             acc[0] = acc[0] * sc + pe * v0[0]; acc[1] = acc[1] * sc + pe * v0[1]; acc[2] = acc[2] * sc + pe * v0[2]; acc[3] = acc[3] * sc + pe * v0[3];
;             acc[4] = acc[4] * sc + pe * v1[0]; acc[5] = acc[5] * sc + pe * v1[1]; acc[6] = acc[6] * sc + pe * v1[2]; acc[7] = acc[7] * sc + pe * v1[3];
;             m = mn;
;         }
	v_fma_f32 v197, v160, v64, v194
	v_fmac_f32_e32 v197, v161, v65
	v_fmac_f32_e32 v197, v162, v66
	v_fmac_f32_e32 v197, v163, v67
	v_fmac_f32_e32 v197, v164, v68
	v_fmac_f32_e32 v197, v165, v69
	v_fmac_f32_e32 v197, v166, v70
	v_fmac_f32_e32 v197, v167, v71
	s_nop 1
	v_add_f32_dpp v197, v197, v197 row_ror:8 row_mask:0xf bank_mask:0xf
	s_nop 1
	v_add_f32_dpp v197, v197, v197 row_ror:4 row_mask:0xf bank_mask:0xf
	s_nop 1
	v_add_f32_dpp v197, v197, v197 row_ror:2 row_mask:0xf bank_mask:0xf
	s_nop 1
	v_add_f32_dpp v197, v197, v197 row_ror:1 row_mask:0xf bank_mask:0xf
	v_max_f32_e32 v198, v192, v197
	v_sub_f32_e32 v199, v192, v198
	v_sub_f32_e32 v200, v197, v198
	v_exp_f32_e32 v199, v199
	v_exp_f32_e32 v200, v200
	v_mov_b32_e32 v192, v198
	v_fma_f32 v193, v193, v199, v200
	v_mul_f32_e32 v168, v168, v199
	v_mul_f32_e32 v169, v169, v199
	v_mul_f32_e32 v170, v170, v199
	v_mul_f32_e32 v171, v171, v199
	v_mul_f32_e32 v172, v172, v199
	v_mul_f32_e32 v173, v173, v199
	v_mul_f32_e32 v174, v174, v199
	v_mul_f32_e32 v175, v175, v199
	v_fmac_f32_e32 v168, v200, v72
	v_fmac_f32_e32 v169, v200, v73
	v_fmac_f32_e32 v170, v200, v74
	v_fmac_f32_e32 v171, v200, v75
	v_fmac_f32_e32 v172, v200, v76
	v_fmac_f32_e32 v173, v200, v77
	v_fmac_f32_e32 v174, v200, v78
	v_fmac_f32_e32 v175, v200, v79
	v_add_f32_e32 v194, v194, v196
	v_add_u32_e32 v195, s42, v195
	global_load_dwordx4 v[64:67], v195, s[20:21]
	global_load_dwordx4 v[68:71], v195, s[20:21] offset:256
	global_load_dwordx4 v[72:75], v195, s[24:25]
	global_load_dwordx4 v[76:79], v195, s[24:25] offset:256
	s_waitcnt vmcnt(28)
	v_fma_f32 v197, v160, v80, v194
	v_fmac_f32_e32 v197, v161, v81
	v_fmac_f32_e32 v197, v162, v82
	v_fmac_f32_e32 v197, v163, v83
	v_fmac_f32_e32 v197, v164, v84
	v_fmac_f32_e32 v197, v165, v85
	v_fmac_f32_e32 v197, v166, v86
	v_fmac_f32_e32 v197, v167, v87
	s_nop 1
	v_add_f32_dpp v197, v197, v197 row_ror:8 row_mask:0xf bank_mask:0xf
	s_nop 1
	v_add_f32_dpp v197, v197, v197 row_ror:4 row_mask:0xf bank_mask:0xf
	s_nop 1
	v_add_f32_dpp v197, v197, v197 row_ror:2 row_mask:0xf bank_mask:0xf
	s_nop 1
	v_add_f32_dpp v197, v197, v197 row_ror:1 row_mask:0xf bank_mask:0xf
	v_max_f32_e32 v198, v192, v197
	v_sub_f32_e32 v199, v192, v198
	v_sub_f32_e32 v200, v197, v198
	v_exp_f32_e32 v199, v199
	v_exp_f32_e32 v200, v200
	v_mov_b32_e32 v192, v198
	v_fma_f32 v193, v193, v199, v200
	v_mul_f32_e32 v168, v168, v199
	v_mul_f32_e32 v169, v169, v199
	v_mul_f32_e32 v170, v170, v199
	v_mul_f32_e32 v171, v171, v199
	v_mul_f32_e32 v172, v172, v199
	v_mul_f32_e32 v173, v173, v199
	v_mul_f32_e32 v174, v174, v199
	v_mul_f32_e32 v175, v175, v199
	v_fmac_f32_e32 v168, v200, v88
	v_fmac_f32_e32 v169, v200, v89
	v_fmac_f32_e32 v170, v200, v90
	v_fmac_f32_e32 v171, v200, v91
	v_fmac_f32_e32 v172, v200, v92
	v_fmac_f32_e32 v173, v200, v93
	v_fmac_f32_e32 v174, v200, v94
	v_fmac_f32_e32 v175, v200, v95
	v_add_f32_e32 v194, v194, v196
	v_add_u32_e32 v195, s42, v195
	global_load_dwordx4 v[80:83], v195, s[20:21]
	global_load_dwordx4 v[84:87], v195, s[20:21] offset:256
	global_load_dwordx4 v[88:91], v195, s[24:25]
	global_load_dwordx4 v[92:95], v195, s[24:25] offset:256
	s_waitcnt vmcnt(28)
	v_fma_f32 v197, v160, v96, v194
	v_fmac_f32_e32 v197, v161, v97
	v_fmac_f32_e32 v197, v162, v98
	v_fmac_f32_e32 v197, v163, v99
	v_fmac_f32_e32 v197, v164, v100
	v_fmac_f32_e32 v197, v165, v101
	v_fmac_f32_e32 v197, v166, v102
	v_fmac_f32_e32 v197, v167, v103
	s_nop 1
	v_add_f32_dpp v197, v197, v197 row_ror:8 row_mask:0xf bank_mask:0xf
	s_nop 1
	v_add_f32_dpp v197, v197, v197 row_ror:4 row_mask:0xf bank_mask:0xf
	s_nop 1
	v_add_f32_dpp v197, v197, v197 row_ror:2 row_mask:0xf bank_mask:0xf
	s_nop 1
	v_add_f32_dpp v197, v197, v197 row_ror:1 row_mask:0xf bank_mask:0xf
	v_max_f32_e32 v198, v192, v197
	v_sub_f32_e32 v199, v192, v198
	v_sub_f32_e32 v200, v197, v198
	v_exp_f32_e32 v199, v199
	v_exp_f32_e32 v200, v200
	v_mov_b32_e32 v192, v198
	v_fma_f32 v193, v193, v199, v200
	v_mul_f32_e32 v168, v168, v199
	v_mul_f32_e32 v169, v169, v199
	v_mul_f32_e32 v170, v170, v199
	v_mul_f32_e32 v171, v171, v199
	v_mul_f32_e32 v172, v172, v199
	v_mul_f32_e32 v173, v173, v199
	v_mul_f32_e32 v174, v174, v199
	v_mul_f32_e32 v175, v175, v199
	v_fmac_f32_e32 v168, v200, v104
	v_fmac_f32_e32 v169, v200, v105
	v_fmac_f32_e32 v170, v200, v106
	v_fmac_f32_e32 v171, v200, v107
	v_fmac_f32_e32 v172, v200, v108
	v_fmac_f32_e32 v173, v200, v109
	v_fmac_f32_e32 v174, v200, v110
	v_fmac_f32_e32 v175, v200, v111
	v_add_f32_e32 v194, v194, v196
	v_add_u32_e32 v195, s42, v195
	global_load_dwordx4 v[96:99], v195, s[20:21]
	global_load_dwordx4 v[100:103], v195, s[20:21] offset:256
	global_load_dwordx4 v[104:107], v195, s[24:25]
	global_load_dwordx4 v[108:111], v195, s[24:25] offset:256
	s_waitcnt vmcnt(28)
	v_fma_f32 v197, v160, v112, v194
	v_fmac_f32_e32 v197, v161, v113
	v_fmac_f32_e32 v197, v162, v114
	v_fmac_f32_e32 v197, v163, v115
	v_fmac_f32_e32 v197, v164, v116
	v_fmac_f32_e32 v197, v165, v117
	v_fmac_f32_e32 v197, v166, v118
	v_fmac_f32_e32 v197, v167, v119
	s_nop 1
	v_add_f32_dpp v197, v197, v197 row_ror:8 row_mask:0xf bank_mask:0xf
	s_nop 1
	v_add_f32_dpp v197, v197, v197 row_ror:4 row_mask:0xf bank_mask:0xf
	s_nop 1
	v_add_f32_dpp v197, v197, v197 row_ror:2 row_mask:0xf bank_mask:0xf
	s_nop 1
	v_add_f32_dpp v197, v197, v197 row_ror:1 row_mask:0xf bank_mask:0xf
	v_max_f32_e32 v198, v192, v197
	v_sub_f32_e32 v199, v192, v198
	v_sub_f32_e32 v200, v197, v198
	v_exp_f32_e32 v199, v199
	v_exp_f32_e32 v200, v200
	v_mov_b32_e32 v192, v198
	v_fma_f32 v193, v193, v199, v200
	v_mul_f32_e32 v168, v168, v199
	v_mul_f32_e32 v169, v169, v199
	v_mul_f32_e32 v170, v170, v199
	v_mul_f32_e32 v171, v171, v199
	v_mul_f32_e32 v172, v172, v199
	v_mul_f32_e32 v173, v173, v199
	v_mul_f32_e32 v174, v174, v199
	v_mul_f32_e32 v175, v175, v199
	v_fmac_f32_e32 v168, v200, v120
	v_fmac_f32_e32 v169, v200, v121
	v_fmac_f32_e32 v170, v200, v122
	v_fmac_f32_e32 v171, v200, v123
	v_fmac_f32_e32 v172, v200, v124
	v_fmac_f32_e32 v173, v200, v125
	v_fmac_f32_e32 v174, v200, v126
	v_fmac_f32_e32 v175, v200, v127
	v_add_f32_e32 v194, v194, v196
	v_add_u32_e32 v195, s42, v195
	global_load_dwordx4 v[112:115], v195, s[20:21]
	global_load_dwordx4 v[116:119], v195, s[20:21] offset:256
	global_load_dwordx4 v[120:123], v195, s[24:25]
	global_load_dwordx4 v[124:127], v195, s[24:25] offset:256
	s_add_u32 s33, s33, 1
	s_cmp_lt_u32 s33, 11
	s_cbranch_scc1 .Las_trip
; __device__ __forceinline__ float fexp2(float x) { return __builtin_amdgcn_exp2f(x); }
; __device__ __forceinline__ void attn_sample_item(const P& p, int wi, int lane) {
;     ...
;         for (int jj = 0; jj < 33; ++jj) {
;             const int j = 4 * jj + kg; const bool valid = j <= 128; const int jc = valid ? j : 128;
;             const int idx = 2048 + i - d * jc;
;             f32x4 k0, k1, v0, v1;
;             if (idx < 2048) { const size_t off = (((size_t)bs * 2048 + idx) * 8 + h) * 128 + 8 * li;
;                 k0 = __builtin_nontemporal_load((const f32x4*)(p.cache_k + off)); k1 = __builtin_nontemporal_load((const f32x4*)(p.cache_k + off + 4)); v0 = __builtin_nontemporal_load((const f32x4*)(p.cache_v + off)); v1 = __builtin_nontemporal_load((const f32x4*)(p.cache_v + off + 4)); }
;             else { const int nr = bs * 4 + (idx - 2048); const float rsn = rstd1[TP + nr]; const int c0 = 4096 + h * 128 + 8 * li;
;                 k0 = acc1_4(ACC1, nr, c0) * rsn; k1 = acc1_4(ACC1, nr, c0 + 4) * rsn; v0 = acc1_4(ACC1, nr, c0 + 1024) * rsn; v1 = acc1_4(ACC1, nr, c0 + 1028) * rsn; }
;             float dot = (q[0] * k0[0] + q[1] * k0[1]) + (q[2] * k0[2] + q[3] * k0[3]) + (q[4] * k1[0] + q[5] * k1[1]) + (q[6] * k1[2] + q[7] * k1[3]);
;             dot += __shfl_xor(dot, 1); dot += __shfl_xor(dot, 2); dot += __shfl_xor(dot, 4); dot += __shfl_xor(dot, 8);
;             const float s = valid ? dot - sl * (float)(d * j) : -INFINITY;
;             const float mn = fmaxf(m, s), sc = fexp2(m - mn), pe = fexp2(s - mn);
;             l = l * sc + pe;
;             acc[0] = acc[0] * sc + pe * v0[0]; acc[1] = acc[1] * sc + pe * v0[1]; acc[2] = acc[2] * sc + pe * v0[2]; acc[3] = acc[3] * sc + pe * v0[3];
;             acc[4] = acc[4] * sc + pe * v1[0]; acc[5] = acc[5] * sc + pe * v1[1]; acc[6] = acc[6] * sc + pe * v1[2]; acc[7] = acc[7] * sc + pe * v1[3];
;             m = mn;
;         }
	s_waitcnt vmcnt(28)
	v_fma_f32 v197, v160, v0, v194
	v_fmac_f32_e32 v197, v161, v1
	v_fmac_f32_e32 v197, v162, v2
	v_fmac_f32_e32 v197, v163, v3
	v_fmac_f32_e32 v197, v164, v4
	v_fmac_f32_e32 v197, v165, v5
	v_fmac_f32_e32 v197, v166, v6
	v_fmac_f32_e32 v197, v167, v7
	s_nop 1
	v_add_f32_dpp v197, v197, v197 row_ror:8 row_mask:0xf bank_mask:0xf
	s_nop 1
	v_add_f32_dpp v197, v197, v197 row_ror:4 row_mask:0xf bank_mask:0xf
	s_nop 1
	v_add_f32_dpp v197, v197, v197 row_ror:2 row_mask:0xf bank_mask:0xf
	s_nop 1
	v_add_f32_dpp v197, v197, v197 row_ror:1 row_mask:0xf bank_mask:0xf
	v_max_f32_e32 v198, v192, v197
	v_sub_f32_e32 v199, v192, v198
	v_sub_f32_e32 v200, v197, v198
	v_exp_f32_e32 v199, v199
	v_exp_f32_e32 v200, v200
	v_mov_b32_e32 v192, v198
	v_fma_f32 v193, v193, v199, v200
	v_mul_f32_e32 v168, v168, v199
	v_mul_f32_e32 v169, v169, v199
	v_mul_f32_e32 v170, v170, v199
	v_mul_f32_e32 v171, v171, v199
	v_mul_f32_e32 v172, v172, v199
	v_mul_f32_e32 v173, v173, v199
	v_mul_f32_e32 v174, v174, v199
	v_mul_f32_e32 v175, v175, v199
	v_fmac_f32_e32 v168, v200, v8
	v_fmac_f32_e32 v169, v200, v9
	v_fmac_f32_e32 v170, v200, v10
	v_fmac_f32_e32 v171, v200, v11
	v_fmac_f32_e32 v172, v200, v12
	v_fmac_f32_e32 v173, v200, v13
	v_fmac_f32_e32 v174, v200, v14
	v_fmac_f32_e32 v175, v200, v15
	v_add_f32_e32 v194, v194, v196
	s_waitcnt vmcnt(24)
	v_fma_f32 v197, v160, v16, v194
	v_fmac_f32_e32 v197, v161, v17
	v_fmac_f32_e32 v197, v162, v18
	v_fmac_f32_e32 v197, v163, v19
	v_fmac_f32_e32 v197, v164, v20
	v_fmac_f32_e32 v197, v165, v21
	v_fmac_f32_e32 v197, v166, v22
	v_fmac_f32_e32 v197, v167, v23
	s_nop 1
	v_add_f32_dpp v197, v197, v197 row_ror:8 row_mask:0xf bank_mask:0xf
	s_nop 1
	v_add_f32_dpp v197, v197, v197 row_ror:4 row_mask:0xf bank_mask:0xf
	s_nop 1
	v_add_f32_dpp v197, v197, v197 row_ror:2 row_mask:0xf bank_mask:0xf
	s_nop 1
	v_add_f32_dpp v197, v197, v197 row_ror:1 row_mask:0xf bank_mask:0xf
	v_max_f32_e32 v198, v192, v197
	v_sub_f32_e32 v199, v192, v198
	v_sub_f32_e32 v200, v197, v198
	v_exp_f32_e32 v199, v199
	v_exp_f32_e32 v200, v200
	v_mov_b32_e32 v192, v198
	v_fma_f32 v193, v193, v199, v200
	v_mul_f32_e32 v168, v168, v199
	v_mul_f32_e32 v169, v169, v199
	v_mul_f32_e32 v170, v170, v199
	v_mul_f32_e32 v171, v171, v199
	v_mul_f32_e32 v172, v172, v199
	v_mul_f32_e32 v173, v173, v199
	v_mul_f32_e32 v174, v174, v199
	v_mul_f32_e32 v175, v175, v199
	v_fmac_f32_e32 v168, v200, v24
	v_fmac_f32_e32 v169, v200, v25
	v_fmac_f32_e32 v170, v200, v26
	v_fmac_f32_e32 v171, v200, v27
	v_fmac_f32_e32 v172, v200, v28
	v_fmac_f32_e32 v173, v200, v29
	v_fmac_f32_e32 v174, v200, v30
	v_fmac_f32_e32 v175, v200, v31
	v_add_f32_e32 v194, v194, v196
	s_waitcnt vmcnt(20)
	v_fma_f32 v197, v160, v32, v194
	v_fmac_f32_e32 v197, v161, v33
	v_fmac_f32_e32 v197, v162, v34
	v_fmac_f32_e32 v197, v163, v35
	v_fmac_f32_e32 v197, v164, v36
	v_fmac_f32_e32 v197, v165, v37
	v_fmac_f32_e32 v197, v166, v38
	v_fmac_f32_e32 v197, v167, v39
	s_nop 1
	v_add_f32_dpp v197, v197, v197 row_ror:8 row_mask:0xf bank_mask:0xf
	s_nop 1
	v_add_f32_dpp v197, v197, v197 row_ror:4 row_mask:0xf bank_mask:0xf
	s_nop 1
	v_add_f32_dpp v197, v197, v197 row_ror:2 row_mask:0xf bank_mask:0xf
	s_nop 1
	v_add_f32_dpp v197, v197, v197 row_ror:1 row_mask:0xf bank_mask:0xf
	v_max_f32_e32 v198, v192, v197
	v_sub_f32_e32 v199, v192, v198
	v_sub_f32_e32 v200, v197, v198
	v_exp_f32_e32 v199, v199
	v_exp_f32_e32 v200, v200
	v_mov_b32_e32 v192, v198
	v_fma_f32 v193, v193, v199, v200
	v_mul_f32_e32 v168, v168, v199
	v_mul_f32_e32 v169, v169, v199
	v_mul_f32_e32 v170, v170, v199
	v_mul_f32_e32 v171, v171, v199
	v_mul_f32_e32 v172, v172, v199
	v_mul_f32_e32 v173, v173, v199
	v_mul_f32_e32 v174, v174, v199
	v_mul_f32_e32 v175, v175, v199
	v_fmac_f32_e32 v168, v200, v40
	v_fmac_f32_e32 v169, v200, v41
	v_fmac_f32_e32 v170, v200, v42
	v_fmac_f32_e32 v171, v200, v43
	v_fmac_f32_e32 v172, v200, v44
	v_fmac_f32_e32 v173, v200, v45
	v_fmac_f32_e32 v174, v200, v46
	v_fmac_f32_e32 v175, v200, v47
	v_add_f32_e32 v194, v194, v196
	s_waitcnt vmcnt(16)
	v_fma_f32 v197, v160, v48, v194
	v_fmac_f32_e32 v197, v161, v49
	v_fmac_f32_e32 v197, v162, v50
	v_fmac_f32_e32 v197, v163, v51
	v_fmac_f32_e32 v197, v164, v52
	v_fmac_f32_e32 v197, v165, v53
	v_fmac_f32_e32 v197, v166, v54
	v_fmac_f32_e32 v197, v167, v55
	s_nop 1
	v_add_f32_dpp v197, v197, v197 row_ror:8 row_mask:0xf bank_mask:0xf
	s_nop 1
	v_add_f32_dpp v197, v197, v197 row_ror:4 row_mask:0xf bank_mask:0xf
	s_nop 1
	v_add_f32_dpp v197, v197, v197 row_ror:2 row_mask:0xf bank_mask:0xf
	s_nop 1
	v_add_f32_dpp v197, v197, v197 row_ror:1 row_mask:0xf bank_mask:0xf
	v_max_f32_e32 v198, v192, v197
	v_sub_f32_e32 v199, v192, v198
	v_sub_f32_e32 v200, v197, v198
	v_exp_f32_e32 v199, v199
	v_exp_f32_e32 v200, v200
	v_mov_b32_e32 v192, v198
	v_fma_f32 v193, v193, v199, v200
	v_mul_f32_e32 v168, v168, v199
	v_mul_f32_e32 v169, v169, v199
	v_mul_f32_e32 v170, v170, v199
	v_mul_f32_e32 v171, v171, v199
	v_mul_f32_e32 v172, v172, v199
	v_mul_f32_e32 v173, v173, v199
	v_mul_f32_e32 v174, v174, v199
	v_mul_f32_e32 v175, v175, v199
	v_fmac_f32_e32 v168, v200, v56
	v_fmac_f32_e32 v169, v200, v57
	v_fmac_f32_e32 v170, v200, v58
	v_fmac_f32_e32 v171, v200, v59
	v_fmac_f32_e32 v172, v200, v60
	v_fmac_f32_e32 v173, v200, v61
	v_fmac_f32_e32 v174, v200, v62
	v_fmac_f32_e32 v175, v200, v63
	v_add_f32_e32 v194, v194, v196
	s_waitcnt vmcnt(12)
; __device__ __forceinline__ float fexp2(float x) { return __builtin_amdgcn_exp2f(x); }
; __device__ __forceinline__ void attn_sample_item(const P& p, int wi, int lane) {
;     ...
;         for (int jj = 0; jj < 33; ++jj) {
;             const int j = 4 * jj + kg; const bool valid = j <= 128; const int jc = valid ? j : 128;
;             const int idx = 2048 + i - d * jc;
;             f32x4 k0, k1, v0, v1;
;             if (idx < 2048) { const size_t off = (((size_t)bs * 2048 + idx) * 8 + h) * 128 + 8 * li;
;                 k0 = __builtin_nontemporal_load((const f32x4*)(p.cache_k + off)); k1 = __builtin_nontemporal_load((const f32x4*)(p.cache_k + off + 4)); v0 = __builtin_nontemporal_load((const f32x4*)(p.cache_v + off)); v1 = __builtin_nontemporal_load((const f32x4*)(p.cache_v + off + 4)); }
;             else { const int nr = bs * 4 + (idx - 2048); const float rsn = rstd1[TP + nr]; const int c0 = 4096 + h * 128 + 8 * li;
;                 k0 = acc1_4(ACC1, nr, c0) * rsn; k1 = acc1_4(ACC1, nr, c0 + 4) * rsn; v0 = acc1_4(ACC1, nr, c0 + 1024) * rsn; v1 = acc1_4(ACC1, nr, c0 + 1028) * rsn; }
;             float dot = (q[0] * k0[0] + q[1] * k0[1]) + (q[2] * k0[2] + q[3] * k0[3]) + (q[4] * k1[0] + q[5] * k1[1]) + (q[6] * k1[2] + q[7] * k1[3]);
;             dot += __shfl_xor(dot, 1); dot += __shfl_xor(dot, 2); dot += __shfl_xor(dot, 4); dot += __shfl_xor(dot, 8);
;             const float s = valid ? dot - sl * (float)(d * j) : -INFINITY;
;             const float mn = fmaxf(m, s), sc = fexp2(m - mn), pe = fexp2(s - mn);
;             l = l * sc + pe;
;             acc[0] = acc[0] * sc + pe * v0[0]; acc[1] = acc[1] * sc + pe * v0[1]; acc[2] = acc[2] * sc + pe * v0[2]; acc[3] = acc[3] * sc + pe * v0[3];
;             acc[4] = acc[4] * sc + pe * v1[0]; acc[5] = acc[5] * sc + pe * v1[1]; acc[6] = acc[6] * sc + pe * v1[2]; acc[7] = acc[7] * sc + pe * v1[3];
;             m = mn;
;         }
	v_fma_f32 v197, v160, v64, v194
	v_fmac_f32_e32 v197, v161, v65
	v_fmac_f32_e32 v197, v162, v66
	v_fmac_f32_e32 v197, v163, v67
	v_fmac_f32_e32 v197, v164, v68
	v_fmac_f32_e32 v197, v165, v69
	v_fmac_f32_e32 v197, v166, v70
	v_fmac_f32_e32 v197, v167, v71
	s_nop 1
	v_add_f32_dpp v197, v197, v197 row_ror:8 row_mask:0xf bank_mask:0xf
	s_nop 1
	v_add_f32_dpp v197, v197, v197 row_ror:4 row_mask:0xf bank_mask:0xf
	s_nop 1
	v_add_f32_dpp v197, v197, v197 row_ror:2 row_mask:0xf bank_mask:0xf
	s_nop 1
	v_add_f32_dpp v197, v197, v197 row_ror:1 row_mask:0xf bank_mask:0xf
	v_max_f32_e32 v198, v192, v197
	v_sub_f32_e32 v199, v192, v198
	v_sub_f32_e32 v200, v197, v198
	v_exp_f32_e32 v199, v199
	v_exp_f32_e32 v200, v200
	v_mov_b32_e32 v192, v198
	v_fma_f32 v193, v193, v199, v200
	v_mul_f32_e32 v168, v168, v199
	v_mul_f32_e32 v169, v169, v199
	v_mul_f32_e32 v170, v170, v199
	v_mul_f32_e32 v171, v171, v199
	v_mul_f32_e32 v172, v172, v199
	v_mul_f32_e32 v173, v173, v199
	v_mul_f32_e32 v174, v174, v199
	v_mul_f32_e32 v175, v175, v199
	v_fmac_f32_e32 v168, v200, v72
	v_fmac_f32_e32 v169, v200, v73
	v_fmac_f32_e32 v170, v200, v74
	v_fmac_f32_e32 v171, v200, v75
	v_fmac_f32_e32 v172, v200, v76
	v_fmac_f32_e32 v173, v200, v77
	v_fmac_f32_e32 v174, v200, v78
	v_fmac_f32_e32 v175, v200, v79
	v_add_f32_e32 v194, v194, v196
	s_waitcnt vmcnt(8)
	v_fma_f32 v197, v160, v80, v194
	v_fmac_f32_e32 v197, v161, v81
	v_fmac_f32_e32 v197, v162, v82
	v_fmac_f32_e32 v197, v163, v83
	v_fmac_f32_e32 v197, v164, v84
	v_fmac_f32_e32 v197, v165, v85
	v_fmac_f32_e32 v197, v166, v86
	v_fmac_f32_e32 v197, v167, v87
	s_nop 1
	v_add_f32_dpp v197, v197, v197 row_ror:8 row_mask:0xf bank_mask:0xf
	s_nop 1
	v_add_f32_dpp v197, v197, v197 row_ror:4 row_mask:0xf bank_mask:0xf
	s_nop 1
	v_add_f32_dpp v197, v197, v197 row_ror:2 row_mask:0xf bank_mask:0xf
	s_nop 1
	v_add_f32_dpp v197, v197, v197 row_ror:1 row_mask:0xf bank_mask:0xf
	v_max_f32_e32 v198, v192, v197
	v_sub_f32_e32 v199, v192, v198
	v_sub_f32_e32 v200, v197, v198
	v_exp_f32_e32 v199, v199
	v_exp_f32_e32 v200, v200
	v_mov_b32_e32 v192, v198
	v_fma_f32 v193, v193, v199, v200
	v_mul_f32_e32 v168, v168, v199
	v_mul_f32_e32 v169, v169, v199
	v_mul_f32_e32 v170, v170, v199
	v_mul_f32_e32 v171, v171, v199
	v_mul_f32_e32 v172, v172, v199
	v_mul_f32_e32 v173, v173, v199
	v_mul_f32_e32 v174, v174, v199
	v_mul_f32_e32 v175, v175, v199
	v_fmac_f32_e32 v168, v200, v88
	v_fmac_f32_e32 v169, v200, v89
	v_fmac_f32_e32 v170, v200, v90
	v_fmac_f32_e32 v171, v200, v91
	v_fmac_f32_e32 v172, v200, v92
	v_fmac_f32_e32 v173, v200, v93
	v_fmac_f32_e32 v174, v200, v94
	v_fmac_f32_e32 v175, v200, v95
	v_add_f32_e32 v194, v194, v196
	s_waitcnt vmcnt(4)
	v_fma_f32 v197, v160, v96, v194
	v_fmac_f32_e32 v197, v161, v97
	v_fmac_f32_e32 v197, v162, v98
	v_fmac_f32_e32 v197, v163, v99
	v_fmac_f32_e32 v197, v164, v100
	v_fmac_f32_e32 v197, v165, v101
	v_fmac_f32_e32 v197, v166, v102
	v_fmac_f32_e32 v197, v167, v103
	s_nop 1
	v_add_f32_dpp v197, v197, v197 row_ror:8 row_mask:0xf bank_mask:0xf
	s_nop 1
	v_add_f32_dpp v197, v197, v197 row_ror:4 row_mask:0xf bank_mask:0xf
	s_nop 1
	v_add_f32_dpp v197, v197, v197 row_ror:2 row_mask:0xf bank_mask:0xf
	s_nop 1
	v_add_f32_dpp v197, v197, v197 row_ror:1 row_mask:0xf bank_mask:0xf
	v_max_f32_e32 v198, v192, v197
	v_sub_f32_e32 v199, v192, v198
	v_sub_f32_e32 v200, v197, v198
	v_exp_f32_e32 v199, v199
	v_exp_f32_e32 v200, v200
	v_mov_b32_e32 v192, v198
	v_fma_f32 v193, v193, v199, v200
	v_mul_f32_e32 v168, v168, v199
	v_mul_f32_e32 v169, v169, v199
	v_mul_f32_e32 v170, v170, v199
	v_mul_f32_e32 v171, v171, v199
	v_mul_f32_e32 v172, v172, v199
	v_mul_f32_e32 v173, v173, v199
	v_mul_f32_e32 v174, v174, v199
	v_mul_f32_e32 v175, v175, v199
	v_fmac_f32_e32 v168, v200, v104
	v_fmac_f32_e32 v169, v200, v105
	v_fmac_f32_e32 v170, v200, v106
	v_fmac_f32_e32 v171, v200, v107
	v_fmac_f32_e32 v172, v200, v108
	v_fmac_f32_e32 v173, v200, v109
	v_fmac_f32_e32 v174, v200, v110
	v_fmac_f32_e32 v175, v200, v111
	v_add_f32_e32 v194, v194, v196
	s_waitcnt vmcnt(0)
; __device__ __forceinline__ float fexp2(float x) { return __builtin_amdgcn_exp2f(x); }
; __device__ __forceinline__ void attn_sample_item(const P& p, int wi, int lane) {
;     ...
;             float dot = (q[0] * k0[0] + q[1] * k0[1]) + (q[2] * k0[2] + q[3] * k0[3]) + (q[4] * k1[0] + q[5] * k1[1]) + (q[6] * k1[2] + q[7] * k1[3]);
;             dot += __shfl_xor(dot, 1); dot += __shfl_xor(dot, 2); dot += __shfl_xor(dot, 4); dot += __shfl_xor(dot, 8);
;             const float s = valid ? dot - sl * (float)(d * j) : -INFINITY;
;             const float mn = fmaxf(m, s), sc = fexp2(m - mn), pe = fexp2(s - mn);
;             l = l * sc + pe;
;             acc[0] = acc[0] * sc + pe * v0[0]; acc[1] = acc[1] * sc + pe * v0[1]; acc[2] = acc[2] * sc + pe * v0[2]; acc[3] = acc[3] * sc + pe * v0[3];
;             acc[4] = acc[4] * sc + pe * v1[0]; acc[5] = acc[5] * sc + pe * v1[1]; acc[6] = acc[6] * sc + pe * v1[2]; acc[7] = acc[7] * sc + pe * v1[3];
;             m = mn;
;         }
;     }
;     float mt = fmaxf(m, __shfl_xor(m, 16)); mt = fmaxf(mt, __shfl_xor(mt, 32));
;     const float f = fexp2(m - mt);
;     l *= f; l += __shfl_xor(l, 16); l += __shfl_xor(l, 32);
;     const float inv = 1.f / l;
;     float* o = (float*)(ws + O_ATTS) + (size_t)srow * 1024 + h * 128 + 8 * li;
; #pragma unroll
;     for (int e = 0; e < 8; ++e) { float a = acc[e] * f; a += __shfl_xor(a, 16); a += __shfl_xor(a, 32); acc[e] = a * inv; }
;     if (kg == 0) { *(f32x4*)o = (f32x4){acc[0], acc[1], acc[2], acc[3]}; *(f32x4*)(o + 4) = (f32x4){acc[4], acc[5], acc[6], acc[7]}; }
	v_fma_f32 v197, v160, v112, v194
	v_fmac_f32_e32 v197, v161, v113
	v_fmac_f32_e32 v197, v162, v114
	v_fmac_f32_e32 v197, v163, v115
	v_fmac_f32_e32 v197, v164, v116
	v_fmac_f32_e32 v197, v165, v117
	v_fmac_f32_e32 v197, v166, v118
	v_fmac_f32_e32 v197, v167, v119
	s_nop 1
	v_add_f32_dpp v197, v197, v197 row_ror:8 row_mask:0xf bank_mask:0xf
	s_nop 1
	v_add_f32_dpp v197, v197, v197 row_ror:4 row_mask:0xf bank_mask:0xf
	s_nop 1
	v_add_f32_dpp v197, v197, v197 row_ror:2 row_mask:0xf bank_mask:0xf
	s_nop 1
	v_add_f32_dpp v197, v197, v197 row_ror:1 row_mask:0xf bank_mask:0xf
	v_max_f32_e32 v198, v192, v197
	v_sub_f32_e32 v199, v192, v198
	v_sub_f32_e32 v200, v197, v198
	v_exp_f32_e32 v199, v199
	v_exp_f32_e32 v200, v200
	v_mov_b32_e32 v192, v198
	v_fma_f32 v193, v193, v199, v200
	v_mul_f32_e32 v168, v168, v199
	v_mul_f32_e32 v169, v169, v199
	v_mul_f32_e32 v170, v170, v199
	v_mul_f32_e32 v171, v171, v199
	v_mul_f32_e32 v172, v172, v199
	v_mul_f32_e32 v173, v173, v199
	v_mul_f32_e32 v174, v174, v199
	v_mul_f32_e32 v175, v175, v199
	v_fmac_f32_e32 v168, v200, v120
	v_fmac_f32_e32 v169, v200, v121
	v_fmac_f32_e32 v170, v200, v122
	v_fmac_f32_e32 v171, v200, v123
	v_fmac_f32_e32 v172, v200, v124
	v_fmac_f32_e32 v173, v200, v125
	v_fmac_f32_e32 v174, v200, v126
	v_fmac_f32_e32 v175, v200, v127
	v_and_b32_e32 v182, 63, v230
	v_xor_b32_e32 v183, 16, v182
	v_lshlrev_b32_e32 v183, 2, v183
	v_xor_b32_e32 v182, 32, v182
	v_lshlrev_b32_e32 v182, 2, v182
	ds_bpermute_b32 v197, v183, v192
	s_waitcnt lgkmcnt(0)
	v_max_f32_e32 v198, v192, v197
	ds_bpermute_b32 v197, v182, v198
	s_waitcnt lgkmcnt(0)
	v_max_f32_e32 v198, v198, v197
	v_sub_f32_e32 v199, v192, v198
	v_exp_f32_e32 v199, v199
	s_nop 0
	v_mul_f32_e32 v193, v193, v199
	v_mul_f32_e32 v168, v168, v199
	v_mul_f32_e32 v169, v169, v199
	v_mul_f32_e32 v170, v170, v199
	v_mul_f32_e32 v171, v171, v199
	v_mul_f32_e32 v172, v172, v199
	v_mul_f32_e32 v173, v173, v199
	v_mul_f32_e32 v174, v174, v199
	v_mul_f32_e32 v175, v175, v199
	ds_bpermute_b32 v0, v183, v193
	ds_bpermute_b32 v1, v183, v168
	ds_bpermute_b32 v2, v183, v169
	ds_bpermute_b32 v3, v183, v170
	ds_bpermute_b32 v4, v183, v171
	ds_bpermute_b32 v5, v183, v172
	ds_bpermute_b32 v6, v183, v173
	ds_bpermute_b32 v7, v183, v174
	ds_bpermute_b32 v8, v183, v175
	s_waitcnt lgkmcnt(0)
	v_add_f32_e32 v193, v193, v0
	v_add_f32_e32 v168, v168, v1
	v_add_f32_e32 v169, v169, v2
	v_add_f32_e32 v170, v170, v3
	v_add_f32_e32 v171, v171, v4
	v_add_f32_e32 v172, v172, v5
	v_add_f32_e32 v173, v173, v6
	v_add_f32_e32 v174, v174, v7
	v_add_f32_e32 v175, v175, v8
	ds_bpermute_b32 v0, v182, v193
	ds_bpermute_b32 v1, v182, v168
	ds_bpermute_b32 v2, v182, v169
	ds_bpermute_b32 v3, v182, v170
	ds_bpermute_b32 v4, v182, v171
	ds_bpermute_b32 v5, v182, v172
	ds_bpermute_b32 v6, v182, v173
	ds_bpermute_b32 v7, v182, v174
	ds_bpermute_b32 v8, v182, v175
	s_waitcnt lgkmcnt(0)
	v_add_f32_e32 v193, v193, v0
	v_add_f32_e32 v168, v168, v1
	v_add_f32_e32 v169, v169, v2
	v_add_f32_e32 v170, v170, v3
	v_add_f32_e32 v171, v171, v4
	v_add_f32_e32 v172, v172, v5
	v_add_f32_e32 v173, v173, v6
	v_add_f32_e32 v174, v174, v7
	v_add_f32_e32 v175, v175, v8
	v_rcp_f32_e32 v197, v193
	s_nop 0
	v_fma_f32 v198, -v193, v197, 1.0
	v_fma_f32 v197, v198, v197, v197
	v_mul_f32_e32 v168, v168, v197
	v_mul_f32_e32 v169, v169, v197
	v_mul_f32_e32 v170, v170, v197
	v_mul_f32_e32 v171, v171, v197
	v_mul_f32_e32 v172, v172, v197
	v_mul_f32_e32 v173, v173, v197
	v_mul_f32_e32 v174, v174, v197
	v_mul_f32_e32 v175, v175, v197
	v_and_b32_e32 v182, 15, v230
	v_lshlrev_b32_e32 v182, 4, v182
	s_lshl_b32 s43, s17, 12
	s_add_u32 s43, s43, s23
	v_add_u32_e32 v182, s43, v182
	s_mov_b64 exec, 0xffff
	global_store_dwordx4 v182, v[168:171], s[30:31]
	global_store_dwordx4 v182, v[172:175], s[30:31] offset:256
	s_mov_b64 exec, -1
	s_add_i32 s3, s3, s77
	s_cmpk_gt_i32 s3, 0x3ff
	s_cbranch_scc0 .Las_item
